# v10 + P4 epilogue without the 128 redundant canonicalizing v_max per tile
# speedup vs baseline: 1.0181x; 1.0030x over previous
; __device__ __forceinline__ unsigned cvt_pk_bf16(float lo, float hi) { unsigned r; asm volatile("v_cvt_pk_bf16_f32 %0, %1, %2" : "=v"(r) : "v"(lo), "v"(hi)); return r; }
;     __device__ __forceinline__ void operator()(const f32x4 (&acc)[2][2][4][2], const Unit& u, int wr, int wc, int fr, int fq) const {
;     ...
;             for (int m = 0; m < 4; ++m) { const int row = row0 + ai * HALF + m * 16; const float rr = r2[ai][m];
;                 bf16_t* rowp = O + ((size_t)u.pm * (ldc / 64) * 256 + (size_t)(row - u.pm * BM)) * 64 + (size_t)(col0 >> 6) * (256 * 64) + (col0 & 63);
; #pragma unroll
;                 for (int bj = 0; bj < 2; ++bj) { f32x4 v0 = acc[ai][bj][m][0], v1 = acc[ai][bj][m][1];
; #pragma unroll
;                     for (int e = 0; e < 4; ++e) { const float a = fmaxf(v0[e], 0.f), b = fmaxf(v1[e], 0.f); v0[e] = a * a * rr; v1[e] = b * b * rr; }
;                     u32x4 w; w.x = cvt_pk_bf16(v0[0], v0[1]); w.y = cvt_pk_bf16(v0[2], v0[3]); w.z = cvt_pk_bf16(v1[0], v1[1]); w.w = cvt_pk_bf16(v1[2], v1[3]);
;                     *(u32x4*)(rowp + (size_t)bj * (2 * 256 * 64)) = w; } }
.Lp4_r2_cached:
	s_lshl_b32 s2, s6, 8
	s_or_b32 s21, s2, s54
	s_nop 0
	s_nop 0
	s_ashr_i32 s31, s30, 31
	v_max_f32_e32 v120, 0, v120
	v_mul_f32_e32 v120, v120, v120
	v_max_f32_e32 v121, 0, v121
	v_max_f32_e32 v122, 0, v122
	v_mul_f32_e32 v121, v121, v121
	v_mul_f32_e32 v122, v122, v122
	v_max_f32_e32 v124, 0, v124
	v_max_f32_e32 v123, 0, v123
	v_mul_f32_e32 v124, v124, v124
	v_mul_f32_e32 v123, v123, v123
	v_max_f32_e32 v112, 0, v112
	v_mul_f32_e32 v112, v112, v112
	v_max_f32_e32 v113, 0, v113
	v_max_f32_e32 v114, 0, v114
	v_mul_f32_e32 v113, v113, v113
	v_mul_f32_e32 v114, v114, v114
	v_max_f32_e32 v116, 0, v116
	v_mul_f32_e32 v116, v116, v116
	v_max_f32_e32 v115, 0, v115
	v_mul_f32_e32 v115, v115, v115
	v_max_f32_e32 v104, 0, v104
	v_mul_f32_e32 v104, v104, v104
	v_max_f32_e32 v105, 0, v105
	v_max_f32_e32 v106, 0, v106
	v_mul_f32_e32 v105, v105, v105
	v_mul_f32_e32 v106, v106, v106
	v_max_f32_e32 v108, 0, v108
	v_max_f32_e32 v107, 0, v107
	v_mul_f32_e32 v108, v108, v108
	v_mul_f32_e32 v107, v107, v107
	v_max_f32_e32 v96, 0, v96
	v_mul_f32_e32 v96, v96, v96
	s_lshl_b64 s[8:9], s[30:31], 21
	v_mul_f32_e32 v124, v124, v245
	s_ashr_i32 s6, s21, 6
	s_ashr_i32 s7, s6, 31
	s_lshl_b64 s[6:7], s[6:7], 15
	s_add_u32 s8, s42, s8
	v_mul_f32_e32 v173, v120, v245
	v_max_f32_e32 v120, 0, v125
	s_addc_u32 s9, s43, s9
	v_mul_f32_e32 v125, v121, v245
	v_max_f32_e32 v121, 0, v126
	v_mul_f32_e32 v126, v122, v245
	v_max_f32_e32 v122, 0, v127
	v_lshl_add_u64 v[130:131], s[8:9], 0, v[144:145]
	v_mul_f32_e32 v120, v120, v120
	v_lshl_add_u64 v[130:131], v[130:131], 0, s[6:7]
	v_mul_f32_e32 v120, v120, v245
	v_mul_f32_e32 v121, v121, v121
	v_mul_f32_e32 v122, v122, v122
	v_lshl_add_u64 v[130:131], v[130:131], 0, v[140:141]
	v_mul_f32_e32 v121, v121, v245
	v_mul_f32_e32 v122, v122, v245
	v_mul_f32_e32 v123, v123, v245
	v_cvt_pk_bf16_f32 v120, v124, v120
	v_cvt_pk_bf16_f32 v121, v121, v122
	v_cvt_pk_bf16_f32 v122, v173, v125
	v_cvt_pk_bf16_f32 v123, v126, v123
	global_store_dwordx4 v[130:131], v[120:123], off
	v_mul_f32_e32 v116, v116, v245
	v_mul_f32_e32 v115, v115, v245
	v_mul_f32_e32 v120, v112, v245
	v_max_f32_e32 v112, 0, v117
	v_mul_f32_e32 v117, v113, v245
	v_max_f32_e32 v113, 0, v118
	v_mul_f32_e32 v118, v114, v245
	v_max_f32_e32 v114, 0, v119
	v_mul_f32_e32 v112, v112, v112
	v_mul_f32_e32 v112, v112, v245
	v_mul_f32_e32 v113, v113, v113
	v_mul_f32_e32 v114, v114, v114
	v_mul_f32_e32 v113, v113, v245
	v_mul_f32_e32 v114, v114, v245
	v_cvt_pk_bf16_f32 v112, v116, v112
	v_add_co_u32_e32 v116, vcc, s49, v130
	v_cvt_pk_bf16_f32 v113, v113, v114
	v_cvt_pk_bf16_f32 v114, v120, v117
	v_cvt_pk_bf16_f32 v115, v118, v115
	v_mul_f32_e32 v108, v108, v246
	s_nop 0
	v_addc_co_u32_e32 v117, vcc, 0, v131, vcc
	global_store_dwordx4 v[116:117], v[112:115], off
	v_mul_f32_e32 v107, v107, v246
	v_max_f32_e32 v97, 0, v97
	v_mul_f32_e32 v114, v104, v246
	v_max_f32_e32 v104, 0, v109
	v_mul_f32_e32 v109, v105, v246
	v_max_f32_e32 v105, 0, v110
	v_mul_f32_e32 v110, v106, v246
	v_max_f32_e32 v106, 0, v111
	v_lshl_add_u64 v[112:113], s[8:9], 0, v[146:147]
	v_mul_f32_e32 v104, v104, v104
	v_lshl_add_u64 v[112:113], v[112:113], 0, s[6:7]
	v_mul_f32_e32 v104, v104, v246
	v_mul_f32_e32 v105, v105, v105
	v_mul_f32_e32 v106, v106, v106
	v_lshl_add_u64 v[112:113], v[112:113], 0, v[140:141]
	v_mul_f32_e32 v105, v105, v246
	v_mul_f32_e32 v106, v106, v246
	v_cvt_pk_bf16_f32 v104, v108, v104
	v_max_f32_e32 v98, 0, v98
	v_cvt_pk_bf16_f32 v105, v105, v106
	v_cvt_pk_bf16_f32 v106, v114, v109
	v_cvt_pk_bf16_f32 v107, v110, v107
	global_store_dwordx4 v[112:113], v[104:107], off
	v_mul_f32_e32 v97, v97, v97
	s_nop 0
	v_mul_f32_e32 v104, v96, v246
	v_max_f32_e32 v96, 0, v101
	v_mul_f32_e32 v98, v98, v98
	v_max_f32_e32 v100, 0, v100
	v_mul_f32_e32 v101, v97, v246
	v_max_f32_e32 v97, 0, v102
	v_mul_f32_e32 v102, v98, v246
	v_max_f32_e32 v98, 0, v103
	v_mul_f32_e32 v100, v100, v100
	v_mul_f32_e32 v96, v96, v96
	v_mul_f32_e32 v100, v100, v246
	v_mul_f32_e32 v96, v96, v246
	v_mul_f32_e32 v97, v97, v97
	v_max_f32_e32 v99, 0, v99
	v_mul_f32_e32 v98, v98, v98
	v_mul_f32_e32 v97, v97, v246
	v_mul_f32_e32 v98, v98, v246
	v_mul_f32_e32 v99, v99, v99
	v_cvt_pk_bf16_f32 v96, v100, v96
	v_add_co_u32_e32 v100, vcc, s49, v112
	v_max_f32_e32 v88, 0, v88
	v_mul_f32_e32 v99, v99, v246
	v_cvt_pk_bf16_f32 v97, v97, v98
	v_cvt_pk_bf16_f32 v98, v104, v101
	v_addc_co_u32_e32 v101, vcc, 0, v113, vcc
	v_mul_f32_e32 v88, v88, v88
	v_max_f32_e32 v89, 0, v89
	v_max_f32_e32 v90, 0, v90
	v_cvt_pk_bf16_f32 v99, v102, v99
	global_store_dwordx4 v[100:101], v[96:99], off
	v_mul_f32_e32 v89, v89, v89
	v_mul_f32_e32 v90, v90, v90
	v_mul_f32_e32 v98, v88, v247
	v_max_f32_e32 v88, 0, v93
	v_mul_f32_e32 v93, v89, v247
	v_max_f32_e32 v89, 0, v94
	v_mul_f32_e32 v94, v90, v247
	v_max_f32_e32 v90, 0, v95
	v_lshl_add_u64 v[96:97], s[8:9], 0, v[148:149]
	v_max_f32_e32 v92, 0, v92
	v_mul_f32_e32 v88, v88, v88
	v_max_f32_e32 v91, 0, v91
	v_lshl_add_u64 v[96:97], v[96:97], 0, s[6:7]
	v_mul_f32_e32 v92, v92, v92
	v_mul_f32_e32 v88, v88, v247
	v_mul_f32_e32 v89, v89, v89
	v_mul_f32_e32 v90, v90, v90
	v_mul_f32_e32 v91, v91, v91
	v_max_f32_e32 v80, 0, v80
	v_lshl_add_u64 v[96:97], v[96:97], 0, v[140:141]
	v_mul_f32_e32 v92, v92, v247
	v_mul_f32_e32 v89, v89, v247
	v_mul_f32_e32 v90, v90, v247
	v_mul_f32_e32 v91, v91, v247
	v_cvt_pk_bf16_f32 v88, v92, v88
	v_mul_f32_e32 v80, v80, v80
	v_max_f32_e32 v81, 0, v81
	v_max_f32_e32 v82, 0, v82
	v_cvt_pk_bf16_f32 v89, v89, v90
	v_cvt_pk_bf16_f32 v90, v98, v93
	v_cvt_pk_bf16_f32 v91, v94, v91
	global_store_dwordx4 v[96:97], v[88:91], off
	v_mul_f32_e32 v81, v81, v81
	s_nop 0
	v_mul_f32_e32 v88, v80, v247
; __device__ __forceinline__ unsigned cvt_pk_bf16(float lo, float hi) { unsigned r; asm volatile("v_cvt_pk_bf16_f32 %0, %1, %2" : "=v"(r) : "v"(lo), "v"(hi)); return r; }
;     __device__ __forceinline__ void operator()(const f32x4 (&acc)[2][2][4][2], const Unit& u, int wr, int wc, int fr, int fq) const {
;     ...
;             for (int m = 0; m < 4; ++m) { const int row = row0 + ai * HALF + m * 16; const float rr = r2[ai][m];
;                 bf16_t* rowp = O + ((size_t)u.pm * (ldc / 64) * 256 + (size_t)(row - u.pm * BM)) * 64 + (size_t)(col0 >> 6) * (256 * 64) + (col0 & 63);
; #pragma unroll
;                 for (int bj = 0; bj < 2; ++bj) { f32x4 v0 = acc[ai][bj][m][0], v1 = acc[ai][bj][m][1];
; #pragma unroll
;                     for (int e = 0; e < 4; ++e) { const float a = fmaxf(v0[e], 0.f), b = fmaxf(v1[e], 0.f); v0[e] = a * a * rr; v1[e] = b * b * rr; }
;                     u32x4 w; w.x = cvt_pk_bf16(v0[0], v0[1]); w.y = cvt_pk_bf16(v0[2], v0[3]); w.z = cvt_pk_bf16(v1[0], v1[1]); w.w = cvt_pk_bf16(v1[2], v1[3]);
;                     *(u32x4*)(rowp + (size_t)bj * (2 * 256 * 64)) = w; } }
	v_max_f32_e32 v80, 0, v85
	v_mul_f32_e32 v82, v82, v82
	v_max_f32_e32 v84, 0, v84
	v_mul_f32_e32 v85, v81, v247
	v_max_f32_e32 v81, 0, v86
	v_mul_f32_e32 v86, v82, v247
	v_max_f32_e32 v82, 0, v87
	v_mul_f32_e32 v84, v84, v84
	v_mul_f32_e32 v80, v80, v80
	v_mul_f32_e32 v84, v84, v247
	v_mul_f32_e32 v80, v80, v247
	v_mul_f32_e32 v81, v81, v81
	v_max_f32_e32 v83, 0, v83
	v_mul_f32_e32 v82, v82, v82
	v_mul_f32_e32 v81, v81, v247
	v_mul_f32_e32 v82, v82, v247
	v_mul_f32_e32 v83, v83, v83
	v_cvt_pk_bf16_f32 v80, v84, v80
	v_add_co_u32_e32 v84, vcc, s49, v96
	v_max_f32_e32 v72, 0, v72
	v_mul_f32_e32 v83, v83, v247
	v_cvt_pk_bf16_f32 v81, v81, v82
	v_cvt_pk_bf16_f32 v82, v88, v85
	v_addc_co_u32_e32 v85, vcc, 0, v97, vcc
	v_mul_f32_e32 v72, v72, v72
	v_max_f32_e32 v73, 0, v73
	v_max_f32_e32 v74, 0, v74
	v_cvt_pk_bf16_f32 v83, v86, v83
	global_store_dwordx4 v[84:85], v[80:83], off
	v_mul_f32_e32 v73, v73, v73
	v_mul_f32_e32 v74, v74, v74
	v_mul_f32_e32 v82, v72, v248
	v_max_f32_e32 v72, 0, v77
	v_mul_f32_e32 v77, v73, v248
	v_max_f32_e32 v73, 0, v78
	v_mul_f32_e32 v78, v74, v248
	v_max_f32_e32 v74, 0, v79
	v_lshl_add_u64 v[80:81], s[8:9], 0, v[150:151]
	v_max_f32_e32 v76, 0, v76
	v_mul_f32_e32 v72, v72, v72
	v_max_f32_e32 v75, 0, v75
	v_lshl_add_u64 v[80:81], v[80:81], 0, s[6:7]
	v_mul_f32_e32 v76, v76, v76
	v_mul_f32_e32 v72, v72, v248
	v_mul_f32_e32 v73, v73, v73
	v_mul_f32_e32 v74, v74, v74
	v_mul_f32_e32 v75, v75, v75
	v_max_f32_e32 v64, 0, v64
	v_lshl_add_u64 v[80:81], v[80:81], 0, v[140:141]
	v_mul_f32_e32 v76, v76, v248
	v_mul_f32_e32 v73, v73, v248
	v_mul_f32_e32 v74, v74, v248
	v_mul_f32_e32 v75, v75, v248
	v_cvt_pk_bf16_f32 v72, v76, v72
	v_mul_f32_e32 v64, v64, v64
	v_max_f32_e32 v65, 0, v65
	v_max_f32_e32 v66, 0, v66
	v_cvt_pk_bf16_f32 v73, v73, v74
	v_cvt_pk_bf16_f32 v74, v82, v77
	v_cvt_pk_bf16_f32 v75, v78, v75
	global_store_dwordx4 v[80:81], v[72:75], off
	v_mul_f32_e32 v65, v65, v65
	s_nop 0
	v_mul_f32_e32 v72, v64, v248
	v_max_f32_e32 v64, 0, v69
	v_mul_f32_e32 v66, v66, v66
	v_max_f32_e32 v68, 0, v68
	v_mul_f32_e32 v69, v65, v248
	v_max_f32_e32 v65, 0, v70
	v_mul_f32_e32 v70, v66, v248
	v_max_f32_e32 v66, 0, v71
	v_mul_f32_e32 v68, v68, v68
	v_mul_f32_e32 v64, v64, v64
	v_mul_f32_e32 v68, v68, v248
	v_mul_f32_e32 v64, v64, v248
	v_mul_f32_e32 v65, v65, v65
	v_max_f32_e32 v67, 0, v67
	v_mul_f32_e32 v66, v66, v66
	v_mul_f32_e32 v65, v65, v248
	v_mul_f32_e32 v66, v66, v248
	v_mul_f32_e32 v67, v67, v67
	v_cvt_pk_bf16_f32 v64, v68, v64
	v_add_co_u32_e32 v68, vcc, s49, v80
	v_max_f32_e32 v56, 0, v56
	v_mul_f32_e32 v67, v67, v248
	v_cvt_pk_bf16_f32 v65, v65, v66
	v_cvt_pk_bf16_f32 v66, v72, v69
	v_addc_co_u32_e32 v69, vcc, 0, v81, vcc
	v_mul_f32_e32 v56, v56, v56
	v_max_f32_e32 v57, 0, v57
	v_max_f32_e32 v58, 0, v58
	v_cvt_pk_bf16_f32 v67, v70, v67
	global_store_dwordx4 v[68:69], v[64:67], off
	v_mul_f32_e32 v57, v57, v57
	v_mul_f32_e32 v58, v58, v58
	v_mul_f32_e32 v66, v56, v249
	v_max_f32_e32 v56, 0, v61
	v_mul_f32_e32 v61, v57, v249
	v_max_f32_e32 v57, 0, v62
	v_mul_f32_e32 v62, v58, v249
	v_max_f32_e32 v58, 0, v63
	v_lshl_add_u64 v[64:65], s[8:9], 0, v[152:153]
	v_max_f32_e32 v60, 0, v60
	v_mul_f32_e32 v56, v56, v56
	v_max_f32_e32 v59, 0, v59
	v_lshl_add_u64 v[64:65], v[64:65], 0, s[6:7]
	v_mul_f32_e32 v60, v60, v60
	v_mul_f32_e32 v56, v56, v249
	v_mul_f32_e32 v57, v57, v57
	v_mul_f32_e32 v58, v58, v58
	v_mul_f32_e32 v59, v59, v59
	v_max_f32_e32 v48, 0, v48
	v_lshl_add_u64 v[64:65], v[64:65], 0, v[140:141]
	v_mul_f32_e32 v60, v60, v249
	v_mul_f32_e32 v57, v57, v249
	v_mul_f32_e32 v58, v58, v249
	v_mul_f32_e32 v59, v59, v249
	v_cvt_pk_bf16_f32 v56, v60, v56
	v_mul_f32_e32 v48, v48, v48
	v_max_f32_e32 v49, 0, v49
	v_max_f32_e32 v50, 0, v50
	v_cvt_pk_bf16_f32 v57, v57, v58
	v_cvt_pk_bf16_f32 v58, v66, v61
	v_cvt_pk_bf16_f32 v59, v62, v59
	global_store_dwordx4 v[64:65], v[56:59], off
	v_mul_f32_e32 v49, v49, v49
	s_nop 0
	v_mul_f32_e32 v56, v48, v249
	v_max_f32_e32 v48, 0, v53
	v_mul_f32_e32 v50, v50, v50
	v_max_f32_e32 v52, 0, v52
	v_mul_f32_e32 v53, v49, v249
	v_max_f32_e32 v49, 0, v54
	v_mul_f32_e32 v54, v50, v249
	v_max_f32_e32 v50, 0, v55
	v_mul_f32_e32 v52, v52, v52
	v_mul_f32_e32 v48, v48, v48
	v_mul_f32_e32 v52, v52, v249
	v_mul_f32_e32 v48, v48, v249
	v_mul_f32_e32 v49, v49, v49
	v_max_f32_e32 v51, 0, v51
	v_mul_f32_e32 v50, v50, v50
	v_mul_f32_e32 v49, v49, v249
	v_mul_f32_e32 v50, v50, v249
	v_mul_f32_e32 v51, v51, v51
	v_cvt_pk_bf16_f32 v48, v52, v48
	v_add_co_u32_e32 v52, vcc, s49, v64
	v_max_f32_e32 v40, 0, v40
	v_mul_f32_e32 v51, v51, v249
	v_cvt_pk_bf16_f32 v49, v49, v50
	v_cvt_pk_bf16_f32 v50, v56, v53
	v_addc_co_u32_e32 v53, vcc, 0, v65, vcc
	v_mul_f32_e32 v40, v40, v40
	v_max_f32_e32 v41, 0, v41
	v_max_f32_e32 v42, 0, v42
	v_cvt_pk_bf16_f32 v51, v54, v51
	global_store_dwordx4 v[52:53], v[48:51], off
	v_mul_f32_e32 v41, v41, v41
	v_mul_f32_e32 v42, v42, v42
	v_mul_f32_e32 v50, v40, v250
	v_max_f32_e32 v40, 0, v45
	v_mul_f32_e32 v45, v41, v250
	v_max_f32_e32 v41, 0, v46
	v_mul_f32_e32 v46, v42, v250
	v_max_f32_e32 v42, 0, v47
	v_lshl_add_u64 v[48:49], s[8:9], 0, v[154:155]
	v_max_f32_e32 v44, 0, v44
	v_mul_f32_e32 v40, v40, v40
	v_max_f32_e32 v43, 0, v43
	v_lshl_add_u64 v[48:49], v[48:49], 0, s[6:7]
	v_mul_f32_e32 v44, v44, v44
	v_mul_f32_e32 v40, v40, v250
	v_mul_f32_e32 v41, v41, v41
	v_mul_f32_e32 v42, v42, v42
; __device__ __forceinline__ unsigned cvt_pk_bf16(float lo, float hi) { unsigned r; asm volatile("v_cvt_pk_bf16_f32 %0, %1, %2" : "=v"(r) : "v"(lo), "v"(hi)); return r; }
; #define PG8_BAR __builtin_amdgcn_s_barrier()
;     __device__ __forceinline__ void operator()(const f32x4 (&acc)[2][2][4][2], const Unit& u, int wr, int wc, int fr, int fq) const {
;     ...
;             for (int m = 0; m < 4; ++m) { const int row = row0 + ai * HALF + m * 16; const float rr = r2[ai][m];
;                 bf16_t* rowp = O + ((size_t)u.pm * (ldc / 64) * 256 + (size_t)(row - u.pm * BM)) * 64 + (size_t)(col0 >> 6) * (256 * 64) + (col0 & 63);
; #pragma unroll
;                 for (int bj = 0; bj < 2; ++bj) { f32x4 v0 = acc[ai][bj][m][0], v1 = acc[ai][bj][m][1];
; #pragma unroll
;                     for (int e = 0; e < 4; ++e) { const float a = fmaxf(v0[e], 0.f), b = fmaxf(v1[e], 0.f); v0[e] = a * a * rr; v1[e] = b * b * rr; }
;                     u32x4 w; w.x = cvt_pk_bf16(v0[0], v0[1]); w.y = cvt_pk_bf16(v0[2], v0[3]); w.z = cvt_pk_bf16(v1[0], v1[1]); w.w = cvt_pk_bf16(v1[2], v1[3]);
;                     *(u32x4*)(rowp + (size_t)bj * (2 * 256 * 64)) = w; } }
; template <class Epi, class Sched, bool ALIGN_EPI = false, bool SP2 = false, bool ABLK = false>
; __device__ __forceinline__ void gemm_phase(PG8_LAS unsigned char* lds, const Gemm g, const Sched& S, const Epi& E) {
;     ...
;         if (!has_next) break;
; #pragma unroll
;         for (int a = 0; a < 2; ++a)
; #pragma unroll
;             for (int b = 0; b < 2; ++b)
; #pragma unroll
;                 for (int m = 0; m < 4; ++m)
; #pragma unroll
;                     for (int n = 0; n < 2; ++n) acc[a][b][m][n] = (f32x4){0.f, 0.f, 0.f, 0.f};
;         cur = nxt; cA = nA; cB = nB; ++ui;
;         if constexpr (ALIGN_EPI) { if (wr == 1) PG8_BAR; }
	v_mul_f32_e32 v43, v43, v43
	v_max_f32_e32 v32, 0, v32
	v_lshl_add_u64 v[48:49], v[48:49], 0, v[140:141]
	v_mul_f32_e32 v44, v44, v250
	v_mul_f32_e32 v41, v41, v250
	v_mul_f32_e32 v42, v42, v250
	v_mul_f32_e32 v43, v43, v250
	v_cvt_pk_bf16_f32 v40, v44, v40
	v_mul_f32_e32 v32, v32, v32
	v_max_f32_e32 v33, 0, v33
	v_max_f32_e32 v34, 0, v34
	v_cvt_pk_bf16_f32 v41, v41, v42
	v_cvt_pk_bf16_f32 v42, v50, v45
	v_cvt_pk_bf16_f32 v43, v46, v43
	global_store_dwordx4 v[48:49], v[40:43], off
	v_mul_f32_e32 v33, v33, v33
	s_nop 0
	v_mul_f32_e32 v40, v32, v250
	v_max_f32_e32 v32, 0, v37
	v_mul_f32_e32 v34, v34, v34
	v_max_f32_e32 v36, 0, v36
	v_mul_f32_e32 v37, v33, v250
	v_max_f32_e32 v33, 0, v38
	v_mul_f32_e32 v38, v34, v250
	v_max_f32_e32 v34, 0, v39
	v_mul_f32_e32 v36, v36, v36
	v_mul_f32_e32 v32, v32, v32
	v_mul_f32_e32 v36, v36, v250
	v_mul_f32_e32 v32, v32, v250
	v_mul_f32_e32 v33, v33, v33
	v_max_f32_e32 v35, 0, v35
	v_mul_f32_e32 v34, v34, v34
	v_mul_f32_e32 v33, v33, v250
	v_mul_f32_e32 v34, v34, v250
	v_mul_f32_e32 v35, v35, v35
	v_cvt_pk_bf16_f32 v32, v36, v32
	v_add_co_u32_e32 v36, vcc, s49, v48
	v_max_f32_e32 v24, 0, v24
	v_mul_f32_e32 v35, v35, v250
	v_cvt_pk_bf16_f32 v33, v33, v34
	v_cvt_pk_bf16_f32 v34, v40, v37
	v_addc_co_u32_e32 v37, vcc, 0, v49, vcc
	v_mul_f32_e32 v24, v24, v24
	v_max_f32_e32 v25, 0, v25
	v_max_f32_e32 v26, 0, v26
	v_cvt_pk_bf16_f32 v35, v38, v35
	global_store_dwordx4 v[36:37], v[32:35], off
	v_mul_f32_e32 v25, v25, v25
	v_mul_f32_e32 v26, v26, v26
	v_mul_f32_e32 v34, v24, v251
	v_max_f32_e32 v24, 0, v29
	v_mul_f32_e32 v29, v25, v251
	v_max_f32_e32 v25, 0, v30
	v_mul_f32_e32 v30, v26, v251
	v_max_f32_e32 v26, 0, v31
	v_lshl_add_u64 v[32:33], s[8:9], 0, v[156:157]
	v_max_f32_e32 v28, 0, v28
	v_mul_f32_e32 v24, v24, v24
	v_max_f32_e32 v27, 0, v27
	v_lshl_add_u64 v[32:33], v[32:33], 0, s[6:7]
	v_mul_f32_e32 v28, v28, v28
	v_mul_f32_e32 v24, v24, v251
	v_mul_f32_e32 v25, v25, v25
	v_mul_f32_e32 v26, v26, v26
	v_mul_f32_e32 v27, v27, v27
	v_max_f32_e32 v16, 0, v16
	v_lshl_add_u64 v[32:33], v[32:33], 0, v[140:141]
	v_mul_f32_e32 v28, v28, v251
	v_mul_f32_e32 v25, v25, v251
	v_mul_f32_e32 v26, v26, v251
	v_mul_f32_e32 v27, v27, v251
	v_cvt_pk_bf16_f32 v24, v28, v24
	v_mul_f32_e32 v16, v16, v16
	v_max_f32_e32 v17, 0, v17
	v_max_f32_e32 v18, 0, v18
	v_cvt_pk_bf16_f32 v25, v25, v26
	v_cvt_pk_bf16_f32 v26, v34, v29
	v_cvt_pk_bf16_f32 v27, v30, v27
	global_store_dwordx4 v[32:33], v[24:27], off
	v_mul_f32_e32 v17, v17, v17
	s_nop 0
	v_mul_f32_e32 v24, v16, v251
	v_max_f32_e32 v16, 0, v21
	v_mul_f32_e32 v18, v18, v18
	v_max_f32_e32 v20, 0, v20
	v_mul_f32_e32 v21, v17, v251
	v_max_f32_e32 v17, 0, v22
	v_mul_f32_e32 v22, v18, v251
	v_max_f32_e32 v18, 0, v23
	v_mul_f32_e32 v20, v20, v20
	v_mul_f32_e32 v16, v16, v16
	v_mul_f32_e32 v20, v20, v251
	v_mul_f32_e32 v16, v16, v251
	v_mul_f32_e32 v17, v17, v17
	v_max_f32_e32 v19, 0, v19
	v_mul_f32_e32 v18, v18, v18
	v_mul_f32_e32 v17, v17, v251
	v_mul_f32_e32 v18, v18, v251
	v_mul_f32_e32 v19, v19, v19
	v_cvt_pk_bf16_f32 v16, v20, v16
	v_add_co_u32_e32 v20, vcc, s49, v32
	v_max_f32_e32 v8, 0, v8
	v_mul_f32_e32 v19, v19, v251
	v_cvt_pk_bf16_f32 v17, v17, v18
	v_cvt_pk_bf16_f32 v18, v24, v21
	v_addc_co_u32_e32 v21, vcc, 0, v33, vcc
	v_mul_f32_e32 v8, v8, v8
	v_max_f32_e32 v9, 0, v9
	v_max_f32_e32 v10, 0, v10
	v_cvt_pk_bf16_f32 v19, v22, v19
	global_store_dwordx4 v[20:21], v[16:19], off
	v_mul_f32_e32 v9, v9, v9
	v_mul_f32_e32 v10, v10, v10
	v_mul_f32_e32 v18, v8, v252
	v_max_f32_e32 v8, 0, v13
	v_mul_f32_e32 v13, v9, v252
	v_max_f32_e32 v9, 0, v14
	v_mul_f32_e32 v14, v10, v252
	v_max_f32_e32 v10, 0, v15
	v_lshl_add_u64 v[16:17], s[8:9], 0, v[158:159]
	v_max_f32_e32 v12, 0, v12
	v_mul_f32_e32 v8, v8, v8
	v_max_f32_e32 v11, 0, v11
	v_lshl_add_u64 v[16:17], v[16:17], 0, s[6:7]
	v_mul_f32_e32 v12, v12, v12
	v_mul_f32_e32 v8, v8, v252
	v_mul_f32_e32 v9, v9, v9
	v_mul_f32_e32 v10, v10, v10
	v_mul_f32_e32 v11, v11, v11
	v_max_f32_e32 v0, 0, v0
	v_lshl_add_u64 v[16:17], v[16:17], 0, v[140:141]
	v_mul_f32_e32 v12, v12, v252
	v_mul_f32_e32 v9, v9, v252
	v_mul_f32_e32 v10, v10, v252
	v_mul_f32_e32 v11, v11, v252
	v_cvt_pk_bf16_f32 v8, v12, v8
	v_mul_f32_e32 v0, v0, v0
	v_max_f32_e32 v1, 0, v1
	v_max_f32_e32 v2, 0, v2
	v_cvt_pk_bf16_f32 v9, v9, v10
	v_cvt_pk_bf16_f32 v10, v18, v13
	v_cvt_pk_bf16_f32 v11, v14, v11
	global_store_dwordx4 v[16:17], v[8:11], off
	v_mul_f32_e32 v1, v1, v1
	s_nop 0
	v_mul_f32_e32 v8, v0, v252
	v_max_f32_e32 v0, 0, v5
	v_mul_f32_e32 v2, v2, v2
	v_max_f32_e32 v4, 0, v4
	v_mul_f32_e32 v5, v1, v252
	v_max_f32_e32 v1, 0, v6
	v_mul_f32_e32 v6, v2, v252
	v_max_f32_e32 v2, 0, v7
	v_mul_f32_e32 v4, v4, v4
	v_mul_f32_e32 v0, v0, v0
	v_mul_f32_e32 v4, v4, v252
	v_mul_f32_e32 v0, v0, v252
	v_mul_f32_e32 v1, v1, v1
	v_mul_f32_e32 v2, v2, v2
	v_mul_f32_e32 v1, v1, v252
	v_max_f32_e32 v3, 0, v3
	v_mul_f32_e32 v2, v2, v252
	v_cvt_pk_bf16_f32 v0, v4, v0
	v_add_co_u32_e32 v4, vcc, 0x10000, v16
	v_mul_f32_e32 v3, v3, v3
	v_cvt_pk_bf16_f32 v1, v1, v2
	v_cvt_pk_bf16_f32 v2, v8, v5
	s_nop 0
	v_addc_co_u32_e32 v5, vcc, 0, v17, vcc
	v_mul_f32_e32 v3, v3, v252
	s_andn2_b64 vcc, exec, s[26:27]
	s_mov_b64 s[6:7], -1
	v_cvt_pk_bf16_f32 v3, v6, v3
	global_store_dwordx4 v[4:5], v[0:3], off
	s_cbranch_vccnz .LBB0_530
	s_andn2_b64 vcc, exec, s[14:15]
	s_cbranch_vccnz .LBB0_529
	s_barrier
	s_branch .LBB0_529
